# v23 + attention mainloop: drop hipcc's vmcnt(1)/vmcnt(0) over-drain after the authors' vmcnt(4) on the prefetch path (drain moved to the no-prefetch edge)
# speedup vs baseline: 1.0062x; 1.0062x over previous
.LBB0_490:
	s_waitcnt lgkmcnt(2)
	v_mfma_f32_32x32x16_bf16 v[48:63], v[112:115], v[100:103], v[48:63]
	ds_read_b64_tr_b16 v[108:109], v226 offset:20480
	ds_read_b64_tr_b16 v[110:111], v226 offset:22528
	ds_read_b64_tr_b16 v[124:125], v226 offset:20992
	ds_read_b64_tr_b16 v[126:127], v226 offset:23040
	v_max3_f32 v100, v80, v81, v64
	v_max3_f32 v101, v82, v83, v65
	v_max3_f32 v100, v100, v66, v67
	v_max3_f32 v100, v100, v84, v85
	v_max3_f32 v101, v101, v86, v87
	v_max3_f32 v100, v100, v68, v69
	s_waitcnt lgkmcnt(4)
	v_mfma_f32_32x32x16_bf16 v[32:47], v[112:115], v[104:107], v[32:47]
	v_max3_f32 v101, v101, v70, v71
	s_nop 0
	v_max_f32_e32 v100, v100, v100
	v_max_f32_e32 v106, v88, v88
	v_max_f32_e32 v100, v100, v106
	v_max3_f32 v101, v101, v90, v91
	v_max3_f32 v100, v100, v89, v72
	v_max3_f32 v101, v101, v74, v75
	v_max3_f32 v100, v100, v73, v92
	v_max3_f32 v101, v101, v94, v95
	v_max3_f32 v100, v100, v93, v76
	v_max3_f32 v101, v101, v78, v79
	v_max3_f32 v100, v100, v77, v101
	v_mov_b32_e32 v101, v100
	s_nop 1
	v_permlane32_swap_b32_e32 v100, v101
	v_max_f32_e32 v101, v101, v101
	v_max_f32_e32 v100, v100, v100
	v_max_f32_e32 v100, v100, v101
	v_sub_f32_e32 v101, v100, v251
	s_mov_b32 s10, 0x42b504f3
	v_cmp_ge_f32_e32 vcc, s10, v101
	v_max_f32_e32 v101, v251, v251
	s_waitcnt lgkmcnt(2)
	v_mfma_f32_32x32x16_bf16 v[48:63], v[120:123], v[108:111], v[48:63]
	v_max_f32_e32 v100, v101, v100
	ds_read_b64_tr_b16 v[102:103], v226 offset:24576
	ds_read_b64_tr_b16 v[104:105], v226 offset:26624
	ds_read_b64_tr_b16 v[196:197], v226 offset:25088
	ds_read_b64_tr_b16 v[198:199], v226 offset:27136
	v_sub_f32_e32 v101, v251, v100
	v_mul_f32_e32 v101, 0x3e0293ee, v101
	v_exp_f32_e32 v101, v101
	s_cmp_eq_u64 vcc, exec
	s_cselect_b64 vcc, -1, 0
	s_waitcnt lgkmcnt(4)
	v_mfma_f32_32x32x16_bf16 v[32:47], v[120:123], v[124:127], v[32:47]
	v_cndmask_b32_e32 v192, v100, v251, vcc
	v_cndmask_b32_e64 v193, v101, 1.0, vcc
	v_mul_f32_e32 v100, 0xbe0293ee, v192
	s_waitcnt lgkmcnt(2)
	v_mfma_f32_32x32x16_bf16 v[48:63], v[116:119], v[102:105], v[48:63]
	ds_read_b64_tr_b16 v[102:103], v226 offset:28672
	ds_read_b64_tr_b16 v[104:105], v226 offset:30720
	ds_read_b64_tr_b16 v[108:109], v226 offset:31232
	ds_read_b64_tr_b16 v[106:107], v226 offset:29184
	v_fmamk_f32 v80, v80, 0x3e0293ee, v100
	v_fmamk_f32 v81, v81, 0x3e0293ee, v100
	v_fmamk_f32 v82, v82, 0x3e0293ee, v100
	v_exp_f32_e32 v80, v80
	v_exp_f32_e32 v81, v81
	v_exp_f32_e32 v82, v82
	s_waitcnt lgkmcnt(4)
	v_mfma_f32_32x32x16_bf16 v[32:47], v[116:119], v[196:199], v[32:47]
	v_fma_f32 v64, v64, s28, v100
	v_fma_f32 v65, v65, s28, v100
	v_fmamk_f32 v66, v66, 0x3e0293ee, v100
	s_waitcnt lgkmcnt(2)
	v_mfma_f32_32x32x16_bf16 v[48:63], v[96:99], v[102:105], v[48:63]
	ds_read_b64_tr_b16 v[124:125], v226 offset:17408
	ds_read_b64_tr_b16 v[126:127], v226 offset:19456
	ds_read_b64_tr_b16 v[196:197], v226 offset:17920
	ds_read_b64_tr_b16 v[198:199], v226 offset:19968
	v_mov_b32_e32 v102, v67
	v_mov_b32_e32 v103, v68
	v_fmamk_f32 v83, v83, 0x3e0293ee, v100
	v_fmamk_f32 v84, v84, 0x3e0293ee, v100
	v_pk_fma_f32 v[102:103], v[102:103], s[28:29], v[100:101] op_sel_hi:[1,0,0]
	v_fmamk_f32 v67, v85, 0x3e0293ee, v100
	s_waitcnt lgkmcnt(4)
	v_mfma_f32_32x32x16_bf16 v[32:47], v[96:99], v[106:109], v[32:47]
	v_exp_f32_e32 v83, v83
	v_exp_f32_e32 v84, v84
	v_exp_f32_e32 v85, v67
	v_fmamk_f32 v69, v69, 0x3e0293ee, v100
	v_mov_b32_e32 v67, v102
	v_mov_b32_e32 v68, v103
	s_waitcnt lgkmcnt(2)
	v_mfma_f32_32x32x16_bf16 v[16:31], v[112:115], v[124:127], v[16:31]
	ds_read_b64_tr_b16 v[102:103], v226 offset:21504
	ds_read_b64_tr_b16 v[104:105], v226 offset:23552
	ds_read_b64_tr_b16 v[108:109], v226 offset:24064
	ds_read_b64_tr_b16 v[106:107], v226 offset:22016
	v_fmamk_f32 v86, v86, 0x3e0293ee, v100
	v_fmamk_f32 v87, v87, 0x3e0293ee, v100
	v_fmamk_f32 v88, v88, 0x3e0293ee, v100
	v_exp_f32_e32 v86, v86
	v_exp_f32_e32 v87, v87
	v_exp_f32_e32 v88, v88
	s_waitcnt lgkmcnt(4)
	v_mfma_f32_32x32x16_bf16 v[0:15], v[112:115], v[196:199], v[0:15]
	v_fma_f32 v70, v70, s28, v100
	v_fma_f32 v71, v71, s28, v100
	v_fmamk_f32 v72, v72, 0x3e0293ee, v100
	s_waitcnt lgkmcnt(2)
	v_mfma_f32_32x32x16_bf16 v[16:31], v[120:123], v[102:105], v[16:31]
	ds_read_b64_tr_b16 v[110:111], v226 offset:25600
	ds_read_b64_tr_b16 v[112:113], v226 offset:27648
	ds_read_b64_tr_b16 v[124:125], v226 offset:26112
	ds_read_b64_tr_b16 v[126:127], v226 offset:28160
	v_mov_b32_e32 v102, v73
	v_mov_b32_e32 v103, v74
	v_fmamk_f32 v89, v89, 0x3e0293ee, v100
	v_fmamk_f32 v90, v90, 0x3e0293ee, v100
	v_pk_fma_f32 v[102:103], v[102:103], s[28:29], v[100:101] op_sel_hi:[1,0,0]
	v_fmamk_f32 v73, v91, 0x3e0293ee, v100
	s_waitcnt lgkmcnt(4)
	v_mfma_f32_32x32x16_bf16 v[0:15], v[120:123], v[106:109], v[0:15]
	v_exp_f32_e32 v89, v89
	v_exp_f32_e32 v90, v90
	v_exp_f32_e32 v91, v73
	v_fmamk_f32 v75, v75, 0x3e0293ee, v100
	v_mov_b32_e32 v73, v102
	v_mov_b32_e32 v74, v103
	s_waitcnt lgkmcnt(2)
	v_mfma_f32_32x32x16_bf16 v[16:31], v[116:119], v[110:113], v[16:31]
	ds_read_b64_tr_b16 v[102:103], v226 offset:29696
	ds_read_b64_tr_b16 v[104:105], v226 offset:31744
	ds_read_b64_tr_b16 v[108:109], v226 offset:32256
	ds_read_b64_tr_b16 v[106:107], v226 offset:30208
	v_fmamk_f32 v92, v92, 0x3e0293ee, v100
	v_fmamk_f32 v93, v93, 0x3e0293ee, v100
	v_exp_f32_e32 v92, v92
	v_exp_f32_e32 v93, v93
	v_pk_fma_f32 v[76:77], v[76:77], s[28:29], v[100:101] op_sel_hi:[1,0,0]
	s_waitcnt lgkmcnt(4)
	v_mfma_f32_32x32x16_bf16 v[0:15], v[116:119], v[124:127], v[0:15]
	s_waitcnt lgkmcnt(2)
	v_mfma_f32_32x32x16_bf16 v[16:31], v[96:99], v[102:105], v[16:31]
	v_mov_b32_e32 v101, v100
	v_fmamk_f32 v94, v94, 0x3e0293ee, v100
	v_fmac_f32_e32 v101, 0x3e0293ee, v95
	v_exp_f32_e32 v94, v94
	v_exp_f32_e32 v95, v101
	v_pk_fma_f32 v[78:79], v[78:79], s[28:29], v[100:101] op_sel_hi:[1,0,0]
	s_waitcnt lgkmcnt(0)
	v_mfma_f32_32x32x16_bf16 v[0:15], v[96:99], v[106:109], v[0:15]
	s_waitcnt vmcnt(4)
	v_cmp_gt_f32_e32 vcc, 1.0, v193
	ds_write_b128 v229, v[184:187] offset:49152
	ds_write_b128 v231, v[188:191] offset:49152
	s_cbranch_vccz .LBB0_494
	s_and_saveexec_b64 s[16:17], s[36:37]
	ds_write_b32 v240, v193 offset:128
	s_or_b64 exec, exec, s[16:17]
	s_waitcnt lgkmcnt(0)
	v_add_u32_e32 v108, s31, v224
	ds_read_b128 v[96:99], v108 offset:224
	ds_read_b128 v[100:103], v108 offset:192
	ds_read_b128 v[104:107], v108 offset:128
	ds_read_b128 v[108:111], v108 offset:160
	s_waitcnt lgkmcnt(3)
	v_pk_mul_f32 v[62:63], v[62:63], v[98:99]
	v_pk_mul_f32 v[60:61], v[60:61], v[96:97]
	s_waitcnt lgkmcnt(2)
	v_pk_mul_f32 v[58:59], v[58:59], v[102:103]
	v_pk_mul_f32 v[56:57], v[56:57], v[100:101]
	s_waitcnt lgkmcnt(0)
	v_pk_mul_f32 v[54:55], v[54:55], v[110:111]
	v_pk_mul_f32 v[52:53], v[52:53], v[108:109]
	v_pk_mul_f32 v[50:51], v[50:51], v[106:107]
	v_pk_mul_f32 v[48:49], v[48:49], v[104:105]
	v_pk_mul_f32 v[46:47], v[46:47], v[98:99]
	v_pk_mul_f32 v[44:45], v[44:45], v[96:97]
	v_pk_mul_f32 v[42:43], v[42:43], v[102:103]
	v_pk_mul_f32 v[40:41], v[40:41], v[100:101]
	v_pk_mul_f32 v[38:39], v[38:39], v[110:111]
	v_pk_mul_f32 v[36:37], v[36:37], v[108:109]
	v_pk_mul_f32 v[34:35], v[34:35], v[106:107]
	v_pk_mul_f32 v[32:33], v[32:33], v[104:105]
	v_pk_mul_f32 v[30:31], v[30:31], v[98:99]
	v_pk_mul_f32 v[28:29], v[28:29], v[96:97]
	v_pk_mul_f32 v[26:27], v[26:27], v[102:103]
	v_pk_mul_f32 v[24:25], v[24:25], v[100:101]
	v_pk_mul_f32 v[22:23], v[22:23], v[110:111]
	v_pk_mul_f32 v[20:21], v[20:21], v[108:109]
	v_pk_mul_f32 v[18:19], v[18:19], v[106:107]
	v_pk_mul_f32 v[16:17], v[16:17], v[104:105]
	v_pk_mul_f32 v[14:15], v[14:15], v[98:99]
	v_pk_mul_f32 v[12:13], v[12:13], v[96:97]
	v_pk_mul_f32 v[10:11], v[10:11], v[102:103]
	v_pk_mul_f32 v[8:9], v[8:9], v[100:101]
	v_pk_mul_f32 v[6:7], v[6:7], v[110:111]
	v_pk_mul_f32 v[4:5], v[4:5], v[108:109]
	v_pk_mul_f32 v[2:3], v[2:3], v[106:107]
	v_pk_mul_f32 v[0:1], v[0:1], v[104:105]

; template <int LD, class FillFn> ...
;     ...
;   for (int j = 1; j + 1 < NT; j += 2) {
;     STEP(pB0, pB1, alB, pA0, pA1, alA, j, 1, true, true);
;     STEP(pA0, pA1, alA, pB0, pB1, alB, j + 1, 0, (j + 3 < NT), true);
.Latt_noprefetch:
	s_waitcnt vmcnt(0)
	s_branch .LBB0_490
